# FFN epilogue: merge-write DPP replaces select pairs (conv row shifts) + previous edits
# speedup vs baseline: 1.0027x; 1.0027x over previous
; __device__ __forceinline__ u32x4 pack8(const float (&f)[8]) { u32x4 w; w.x = cvt_pk_bf16(f[0], f[1]); w.y = cvt_pk_bf16(f[2], f[3]); w.z = cvt_pk_bf16(f[4], f[5]); w.w = cvt_pk_bf16(f[6], f[7]); return w; }
; __device__ __forceinline__ float dpp_row_shr1(float x) { return __int_as_float(__builtin_amdgcn_update_dpp(0, __float_as_int(x), 0x111, 0xf, 0xf, false)); }
; __device__ __forceinline__ float dpp_row_shr2(float x) { return __int_as_float(__builtin_amdgcn_update_dpp(0, __float_as_int(x), 0x112, 0xf, 0xf, false)); }
; __device__ __forceinline__ float dpp_row_ror1(float x) { return __int_as_float(__builtin_amdgcn_update_dpp(0, __float_as_int(x), 0x121, 0xf, 0xf, false)); }
; __device__ __forceinline__ f32x2 gelu_tanh_mul2(f32x2 gt, f32x2 up) {
;     const f32x2 g2 = gt * gt;
;     const f32x2 t = gt * (g2 * 0.044715f + 1.0f);
;     const f32x2 sx = t * (-2.0f * 0.7978845608028654f * 1.4426950408889634f);
;     f32x2 e; e.x = __builtin_amdgcn_exp2f(sx.x); e.y = __builtin_amdgcn_exp2f(sx.y);
;     const f32x2 d = e + 1.0f;
;     f32x2 r; r.x = __builtin_amdgcn_rcpf(d.x); r.y = __builtin_amdgcn_rcpf(d.y);
;     return gt * r * up;
; }
;     __device__ __forceinline__ void operator()(const f32x4 (&acc)[2][2][4][2], const Unit& u, int wr, int wc, int fr, int fq) const {
;     ...
;                     float p1a[8], p2a[8];
; #pragma unroll
;                     for (int e = 0; e < 8; ++e) { const float pv = (e < 4) ? acc[ai][0][m - 1][0][e & 3] : acc[ai][0][m - 1][1][e & 3];
;                         const float s1 = dpp_row_shr1(g8[e]), s2 = dpp_row_shr2(g8[e]), r1 = dpp_row_ror1(pv), r2 = dpp_row_ror2(pv);
;                         p1a[e] = (fr >= 1) ? s1 : r1; p2a[e] = (fr >= 2) ? s2 : r2; }
; #pragma unroll
;                     for (int e = 0; e < 8; e += 2) { const f32x2 gt = (f32x2){w0[e], w0[e + 1]} * (f32x2){p2a[e], p2a[e + 1]} + (f32x2){w1[e], w1[e + 1]} * (f32x2){p1a[e], p1a[e + 1]} + (f32x2){w2[e], w2[e + 1]} * (f32x2){g8[e], g8[e + 1]} + (f32x2){bb[e], bb[e + 1]};
;                         const f32x2 r = gelu_tanh_mul2(gt, (f32x2){u8[e], u8[e + 1]}); o[e] = r.x; o[e + 1] = r.y; }
;                 }
;                 const int rloc = 128 * ai + 64 * wr + 16 * m + fr;
;                 if (!(B == 0 && m == 0 && fr < 2)) *(u32x4*)(ACT + (size_t)(u.pm * BM + rloc) * FF + chg) = pack8(o);
.LBB0_84:
	s_andn2_saveexec_b64 s[30:31], s[30:31]
	s_or_b64 exec, exec, s[30:31]
	s_nop 0
	s_nop 0
	v_mov_b32_dpp v154, v150 row_ror:2 row_mask:0xf bank_mask:0xf
	v_mov_b32_dpp v155, v151 row_ror:2 row_mask:0xf bank_mask:0xf
	v_mov_b32_dpp v156, v152 row_ror:2 row_mask:0xf bank_mask:0xf
	v_mov_b32_dpp v157, v153 row_ror:2 row_mask:0xf bank_mask:0xf
	v_mov_b32_dpp v150, v150 row_ror:1 row_mask:0xf bank_mask:0xf
	v_mov_b32_dpp v151, v151 row_ror:1 row_mask:0xf bank_mask:0xf
	v_mov_b32_dpp v152, v152 row_ror:1 row_mask:0xf bank_mask:0xf
	v_mov_b32_dpp v153, v153 row_ror:1 row_mask:0xf bank_mask:0xf
	v_mov_b32_dpp v154, v134 row_shr:2 row_mask:0xf bank_mask:0xf
	v_mov_b32_dpp v155, v135 row_shr:2 row_mask:0xf bank_mask:0xf
	v_mov_b32_dpp v156, v136 row_shr:2 row_mask:0xf bank_mask:0xf
	v_mov_b32_dpp v157, v137 row_shr:2 row_mask:0xf bank_mask:0xf
	v_mov_b32_dpp v150, v134 row_shr:1 row_mask:0xf bank_mask:0xf
	v_mov_b32_dpp v151, v135 row_shr:1 row_mask:0xf bank_mask:0xf
	v_mov_b32_dpp v152, v136 row_shr:1 row_mask:0xf bank_mask:0xf
	v_mov_b32_dpp v153, v137 row_shr:1 row_mask:0xf bank_mask:0xf
	s_waitcnt vmcnt(0)
	v_pk_mul_f32 v[154:155], v[90:91], v[154:155]
	v_pk_mul_f32 v[156:157], v[92:93], v[156:157]
	v_pk_fma_f32 v[150:151], v[94:95], v[150:151], v[154:155]
	v_pk_fma_f32 v[152:153], v[96:97], v[152:153], v[156:157]
	v_pk_fma_f32 v[150:151], v[134:135], v[98:99], v[150:151]
	v_pk_fma_f32 v[152:153], v[136:137], v[100:101], v[152:153]
	v_pk_add_f32 v[150:151], v[102:103], v[150:151]
	v_pk_add_f32 v[152:153], v[104:105], v[152:153]
	v_pk_mul_f32 v[154:155], v[150:151], v[150:151]
	v_pk_mul_f32 v[156:157], v[152:153], v[152:153]
	v_pk_fma_f32 v[154:155], v[154:155], s[78:79], 1.0 op_sel_hi:[1,0,0]
	v_pk_fma_f32 v[156:157], v[156:157], s[78:79], 1.0 op_sel_hi:[1,0,0]
	v_pk_mul_f32 v[154:155], v[150:151], v[154:155]
	v_pk_mul_f32 v[156:157], v[152:153], v[156:157]
	v_pk_mul_f32 v[154:155], v[154:155], s[24:25] op_sel_hi:[1,0]
	v_pk_mul_f32 v[156:157], v[156:157], s[24:25] op_sel_hi:[1,0]
	v_exp_f32_e32 v154, v154
	v_exp_f32_e32 v155, v155
	v_exp_f32_e32 v156, v156
	v_exp_f32_e32 v157, v157
	v_mov_b32_dpp v158, v146 row_ror:2 row_mask:0xf bank_mask:0xf
	v_mov_b32_dpp v159, v147 row_ror:2 row_mask:0xf bank_mask:0xf
	v_mov_b32_dpp v160, v148 row_ror:2 row_mask:0xf bank_mask:0xf
	v_mov_b32_dpp v161, v149 row_ror:2 row_mask:0xf bank_mask:0xf
	v_mov_b32_dpp v146, v146 row_ror:1 row_mask:0xf bank_mask:0xf
	v_mov_b32_dpp v147, v147 row_ror:1 row_mask:0xf bank_mask:0xf
	v_mov_b32_dpp v148, v148 row_ror:1 row_mask:0xf bank_mask:0xf
	v_mov_b32_dpp v149, v149 row_ror:1 row_mask:0xf bank_mask:0xf
	v_mov_b32_dpp v158, v130 row_shr:2 row_mask:0xf bank_mask:0xf
	v_mov_b32_dpp v159, v131 row_shr:2 row_mask:0xf bank_mask:0xf
	v_mov_b32_dpp v160, v132 row_shr:2 row_mask:0xf bank_mask:0xf
	v_mov_b32_dpp v161, v133 row_shr:2 row_mask:0xf bank_mask:0xf
	v_mov_b32_dpp v146, v130 row_shr:1 row_mask:0xf bank_mask:0xf
	v_mov_b32_dpp v147, v131 row_shr:1 row_mask:0xf bank_mask:0xf
	v_mov_b32_dpp v148, v132 row_shr:1 row_mask:0xf bank_mask:0xf
	v_mov_b32_dpp v149, v133 row_shr:1 row_mask:0xf bank_mask:0xf
	s_waitcnt lgkmcnt(3)
	v_pk_add_f32 v[154:155], v[154:155], 1.0 op_sel_hi:[1,0]
	v_rcp_f32_e32 v154, v154
	v_rcp_f32_e32 v155, v155
	v_pk_add_f32 v[156:157], v[156:157], 1.0 op_sel_hi:[1,0]
	v_rcp_f32_e32 v156, v156
	v_rcp_f32_e32 v157, v157
	v_pk_mul_f32 v[150:151], v[150:151], v[154:155]
	v_pk_mul_f32 v[142:143], v[142:143], v[150:151]
	v_pk_mul_f32 v[150:151], v[152:153], v[156:157]
	v_pk_mul_f32 v[152:153], v[66:67], v[158:159]
	v_pk_mul_f32 v[154:155], v[68:69], v[160:161]
	v_pk_fma_f32 v[146:147], v[70:71], v[146:147], v[152:153]
	v_pk_fma_f32 v[148:149], v[72:73], v[148:149], v[154:155]
	v_pk_fma_f32 v[146:147], v[130:131], v[74:75], v[146:147]
	v_pk_fma_f32 v[148:149], v[132:133], v[76:77], v[148:149]
	v_pk_add_f32 v[146:147], v[78:79], v[146:147]
	v_pk_add_f32 v[148:149], v[80:81], v[148:149]
	v_pk_mul_f32 v[152:153], v[146:147], v[146:147]
	v_pk_mul_f32 v[154:155], v[148:149], v[148:149]
	v_pk_fma_f32 v[152:153], v[152:153], s[78:79], 1.0 op_sel_hi:[1,0,0]
	v_pk_fma_f32 v[154:155], v[154:155], s[78:79], 1.0 op_sel_hi:[1,0,0]
	v_pk_mul_f32 v[152:153], v[146:147], v[152:153]
	v_pk_mul_f32 v[154:155], v[148:149], v[154:155]
	v_pk_mul_f32 v[152:153], v[152:153], s[24:25] op_sel_hi:[1,0]
	v_pk_mul_f32 v[154:155], v[154:155], s[24:25] op_sel_hi:[1,0]
	v_exp_f32_e32 v152, v152
	v_exp_f32_e32 v153, v153
	v_exp_f32_e32 v154, v154
	v_exp_f32_e32 v155, v155
	v_readlane_b32 s8, v253, 57
	v_pk_add_f32 v[152:153], v[152:153], 1.0 op_sel_hi:[1,0]
	v_pk_mul_f32 v[144:145], v[144:145], v[150:151]
	v_rcp_f32_e32 v152, v152
	v_rcp_f32_e32 v153, v153
	v_pk_add_f32 v[154:155], v[154:155], 1.0 op_sel_hi:[1,0]
	v_readlane_b32 s9, v253, 58
	v_rcp_f32_e32 v154, v154
	v_rcp_f32_e32 v155, v155
	v_pk_mul_f32 v[146:147], v[146:147], v[152:153]
	v_cvt_pk_bf16_f32 v142, v142, v143
	v_cvt_pk_bf16_f32 v143, v144, v145
	s_movk_i32 s7, 0x1600
	v_pk_mul_f32 v[138:139], v[138:139], v[146:147]
	v_pk_mul_f32 v[146:147], v[148:149], v[154:155]
	v_cvt_pk_bf16_f32 v144, v138, v139
	v_or_b32_e32 v138, 16, v210
	v_pk_mul_f32 v[140:141], v[140:141], v[146:147]
	v_mov_b32_e32 v148, v195
	v_cvt_pk_bf16_f32 v145, v140, v141
	v_mov_b64_e32 v[140:141], s[8:9]
	v_mad_i64_i32 v[146:147], s[8:9], v138, s7, v[140:141]
	v_lshlrev_b64 v[138:139], 1, v[192:193]
	v_lshl_add_u64 v[146:147], v[146:147], 0, v[138:139]
	global_store_dwordx4 v[146:147], v[142:145], off
	s_nop 0
	s_nop 0
	s_nop 0
	s_nop 0
	v_mov_b32_dpp v142, v134 row_ror:2 row_mask:0xf bank_mask:0xf
	v_mov_b32_dpp v143, v135 row_ror:2 row_mask:0xf bank_mask:0xf
; __device__ __forceinline__ u32x4 pack8(const float (&f)[8]) { u32x4 w; w.x = cvt_pk_bf16(f[0], f[1]); w.y = cvt_pk_bf16(f[2], f[3]); w.z = cvt_pk_bf16(f[4], f[5]); w.w = cvt_pk_bf16(f[6], f[7]); return w; }
; __device__ __forceinline__ float dpp_row_shr1(float x) { return __int_as_float(__builtin_amdgcn_update_dpp(0, __float_as_int(x), 0x111, 0xf, 0xf, false)); }
; __device__ __forceinline__ float dpp_row_shr2(float x) { return __int_as_float(__builtin_amdgcn_update_dpp(0, __float_as_int(x), 0x112, 0xf, 0xf, false)); }
; __device__ __forceinline__ float dpp_row_ror1(float x) { return __int_as_float(__builtin_amdgcn_update_dpp(0, __float_as_int(x), 0x121, 0xf, 0xf, false)); }
; __device__ __forceinline__ f32x2 gelu_tanh_mul2(f32x2 gt, f32x2 up) {
;     const f32x2 g2 = gt * gt;
;     const f32x2 t = gt * (g2 * 0.044715f + 1.0f);
;     const f32x2 sx = t * (-2.0f * 0.7978845608028654f * 1.4426950408889634f);
;     f32x2 e; e.x = __builtin_amdgcn_exp2f(sx.x); e.y = __builtin_amdgcn_exp2f(sx.y);
;     const f32x2 d = e + 1.0f;
;     f32x2 r; r.x = __builtin_amdgcn_rcpf(d.x); r.y = __builtin_amdgcn_rcpf(d.y);
;     return gt * r * up;
; }
;     __device__ __forceinline__ void operator()(const f32x4 (&acc)[2][2][4][2], const Unit& u, int wr, int wc, int fr, int fq) const {
;     ...
;                     float p1a[8], p2a[8];
; #pragma unroll
;                     for (int e = 0; e < 8; ++e) { const float pv = (e < 4) ? acc[ai][0][m - 1][0][e & 3] : acc[ai][0][m - 1][1][e & 3];
;                         const float s1 = dpp_row_shr1(g8[e]), s2 = dpp_row_shr2(g8[e]), r1 = dpp_row_ror1(pv), r2 = dpp_row_ror2(pv);
;                         p1a[e] = (fr >= 1) ? s1 : r1; p2a[e] = (fr >= 2) ? s2 : r2; }
; #pragma unroll
;                     for (int e = 0; e < 8; e += 2) { const f32x2 gt = (f32x2){w0[e], w0[e + 1]} * (f32x2){p2a[e], p2a[e + 1]} + (f32x2){w1[e], w1[e + 1]} * (f32x2){p1a[e], p1a[e + 1]} + (f32x2){w2[e], w2[e + 1]} * (f32x2){g8[e], g8[e + 1]} + (f32x2){bb[e], bb[e + 1]};
;                         const f32x2 r = gelu_tanh_mul2(gt, (f32x2){u8[e], u8[e + 1]}); o[e] = r.x; o[e + 1] = r.y; }
;                 }
;                 const int rloc = 128 * ai + 64 * wr + 16 * m + fr;
;                 if (!(B == 0 && m == 0 && fr < 2)) *(u32x4*)(ACT + (size_t)(u.pm * BM + rloc) * FF + chg) = pack8(o);
	v_mov_b32_dpp v144, v136 row_ror:2 row_mask:0xf bank_mask:0xf
	v_mov_b32_dpp v145, v137 row_ror:2 row_mask:0xf bank_mask:0xf
	v_mov_b32_dpp v134, v134 row_ror:1 row_mask:0xf bank_mask:0xf
	v_mov_b32_dpp v135, v135 row_ror:1 row_mask:0xf bank_mask:0xf
	v_mov_b32_dpp v136, v136 row_ror:1 row_mask:0xf bank_mask:0xf
	v_mov_b32_dpp v137, v137 row_ror:1 row_mask:0xf bank_mask:0xf
	v_mov_b32_dpp v142, v118 row_shr:2 row_mask:0xf bank_mask:0xf
	v_mov_b32_dpp v143, v119 row_shr:2 row_mask:0xf bank_mask:0xf
	v_mov_b32_dpp v144, v120 row_shr:2 row_mask:0xf bank_mask:0xf
	v_mov_b32_dpp v145, v121 row_shr:2 row_mask:0xf bank_mask:0xf
	v_mov_b32_dpp v134, v118 row_shr:1 row_mask:0xf bank_mask:0xf
	v_mov_b32_dpp v135, v119 row_shr:1 row_mask:0xf bank_mask:0xf
	v_mov_b32_dpp v136, v120 row_shr:1 row_mask:0xf bank_mask:0xf
	v_mov_b32_dpp v137, v121 row_shr:1 row_mask:0xf bank_mask:0xf
	v_pk_mul_f32 v[142:143], v[90:91], v[142:143]
	v_pk_mul_f32 v[144:145], v[92:93], v[144:145]
	v_pk_fma_f32 v[134:135], v[94:95], v[134:135], v[142:143]
	v_pk_fma_f32 v[136:137], v[96:97], v[136:137], v[144:145]
	v_pk_fma_f32 v[134:135], v[118:119], v[98:99], v[134:135]
	v_pk_fma_f32 v[136:137], v[120:121], v[100:101], v[136:137]
	v_pk_add_f32 v[134:135], v[102:103], v[134:135]
	v_pk_add_f32 v[136:137], v[104:105], v[136:137]
	v_pk_mul_f32 v[142:143], v[134:135], v[134:135]
	v_pk_mul_f32 v[144:145], v[136:137], v[136:137]
	v_pk_fma_f32 v[142:143], v[142:143], s[78:79], 1.0 op_sel_hi:[1,0,0]
	v_pk_fma_f32 v[144:145], v[144:145], s[78:79], 1.0 op_sel_hi:[1,0,0]
	v_pk_mul_f32 v[142:143], v[134:135], v[142:143]
	v_pk_mul_f32 v[144:145], v[136:137], v[144:145]
	v_pk_mul_f32 v[142:143], v[142:143], s[24:25] op_sel_hi:[1,0]
	v_pk_mul_f32 v[144:145], v[144:145], s[24:25] op_sel_hi:[1,0]
	v_exp_f32_e32 v142, v142
	v_exp_f32_e32 v143, v143
	v_exp_f32_e32 v144, v144
	v_exp_f32_e32 v145, v145
	v_mov_b32_dpp v146, v130 row_ror:2 row_mask:0xf bank_mask:0xf
	v_mov_b32_dpp v147, v131 row_ror:2 row_mask:0xf bank_mask:0xf
	v_mov_b32_dpp v148, v132 row_ror:2 row_mask:0xf bank_mask:0xf
	v_mov_b32_dpp v149, v133 row_ror:2 row_mask:0xf bank_mask:0xf
	v_mov_b32_dpp v130, v130 row_ror:1 row_mask:0xf bank_mask:0xf
	v_mov_b32_dpp v131, v131 row_ror:1 row_mask:0xf bank_mask:0xf
	v_mov_b32_dpp v132, v132 row_ror:1 row_mask:0xf bank_mask:0xf
	v_mov_b32_dpp v133, v133 row_ror:1 row_mask:0xf bank_mask:0xf
	v_mov_b32_dpp v146, v114 row_shr:2 row_mask:0xf bank_mask:0xf
	v_mov_b32_dpp v147, v115 row_shr:2 row_mask:0xf bank_mask:0xf
	v_mov_b32_dpp v148, v116 row_shr:2 row_mask:0xf bank_mask:0xf
	v_mov_b32_dpp v149, v117 row_shr:2 row_mask:0xf bank_mask:0xf
	v_mov_b32_dpp v130, v114 row_shr:1 row_mask:0xf bank_mask:0xf
	v_mov_b32_dpp v131, v115 row_shr:1 row_mask:0xf bank_mask:0xf
	v_mov_b32_dpp v132, v116 row_shr:1 row_mask:0xf bank_mask:0xf
	v_mov_b32_dpp v133, v117 row_shr:1 row_mask:0xf bank_mask:0xf
	v_pk_add_f32 v[142:143], v[142:143], 1.0 op_sel_hi:[1,0]
	v_rcp_f32_e32 v142, v142
	v_rcp_f32_e32 v143, v143
	v_pk_add_f32 v[144:145], v[144:145], 1.0 op_sel_hi:[1,0]
	v_rcp_f32_e32 v144, v144
	v_rcp_f32_e32 v145, v145
	v_pk_mul_f32 v[134:135], v[134:135], v[142:143]
	v_pk_mul_f32 v[126:127], v[126:127], v[134:135]
	v_pk_mul_f32 v[134:135], v[136:137], v[144:145]
	v_pk_mul_f32 v[136:137], v[66:67], v[146:147]
	v_pk_mul_f32 v[142:143], v[68:69], v[148:149]
	v_pk_fma_f32 v[130:131], v[70:71], v[130:131], v[136:137]
	v_pk_fma_f32 v[132:133], v[72:73], v[132:133], v[142:143]
	v_pk_fma_f32 v[130:131], v[114:115], v[74:75], v[130:131]
	v_pk_fma_f32 v[132:133], v[116:117], v[76:77], v[132:133]
	v_pk_add_f32 v[130:131], v[78:79], v[130:131]
	v_pk_add_f32 v[132:133], v[80:81], v[132:133]
	v_pk_mul_f32 v[136:137], v[130:131], v[130:131]
	v_pk_mul_f32 v[142:143], v[132:133], v[132:133]
	v_pk_fma_f32 v[136:137], v[136:137], s[78:79], 1.0 op_sel_hi:[1,0,0]
	v_pk_fma_f32 v[142:143], v[142:143], s[78:79], 1.0 op_sel_hi:[1,0,0]
	v_pk_mul_f32 v[136:137], v[130:131], v[136:137]
	v_pk_mul_f32 v[142:143], v[132:133], v[142:143]
	v_pk_mul_f32 v[136:137], v[136:137], s[24:25] op_sel_hi:[1,0]
	v_pk_mul_f32 v[142:143], v[142:143], s[24:25] op_sel_hi:[1,0]
	v_exp_f32_e32 v136, v136
	v_exp_f32_e32 v137, v137
	v_exp_f32_e32 v142, v142
	v_exp_f32_e32 v143, v143
	v_pk_mul_f32 v[128:129], v[128:129], v[134:135]
	v_pk_add_f32 v[136:137], v[136:137], 1.0 op_sel_hi:[1,0]
	s_movk_i32 s10, 0x1600
	v_rcp_f32_e32 v136, v136
	v_rcp_f32_e32 v137, v137
	v_pk_add_f32 v[142:143], v[142:143], 1.0 op_sel_hi:[1,0]
	s_andn2_b64 vcc, exec, s[62:63]
	v_rcp_f32_e32 v142, v142
	v_rcp_f32_e32 v143, v143
	v_pk_mul_f32 v[130:131], v[130:131], v[136:137]
	s_nop 0
	v_pk_mul_f32 v[130:131], v[122:123], v[130:131]
	v_pk_mul_f32 v[122:123], v[132:133], v[142:143]
	s_nop 0
	v_pk_mul_f32 v[132:133], v[124:125], v[122:123]
	v_cvt_pk_bf16_f32 v122, v126, v127
	v_or_b32_e32 v126, 32, v210
	v_mad_i64_i32 v[126:127], s[8:9], v126, s7, v[140:141]
	v_cvt_pk_bf16_f32 v123, v128, v129
	v_cvt_pk_bf16_f32 v124, v130, v131
	v_cvt_pk_bf16_f32 v125, v132, v133
	v_lshl_add_u64 v[126:127], v[126:127], 0, v[138:139]
	global_store_dwordx4 v[126:127], v[122:125], off
	s_nop 0
	s_nop 0
	s_nop 0
	s_nop 0
	v_mov_b32_dpp v122, v118 row_ror:2 row_mask:0xf bank_mask:0xf
	v_mov_b32_dpp v123, v119 row_ror:2 row_mask:0xf bank_mask:0xf
	v_mov_b32_dpp v124, v120 row_ror:2 row_mask:0xf bank_mask:0xf
	v_mov_b32_dpp v125, v121 row_ror:2 row_mask:0xf bank_mask:0xf
; #define LAS __attribute__((address_space(3)))
; __device__ __forceinline__ u32x4 pack8(const float (&f)[8]) { u32x4 w; w.x = cvt_pk_bf16(f[0], f[1]); w.y = cvt_pk_bf16(f[2], f[3]); w.z = cvt_pk_bf16(f[4], f[5]); w.w = cvt_pk_bf16(f[6], f[7]); return w; }
; __device__ __forceinline__ float dpp_row_shr1(float x) { return __int_as_float(__builtin_amdgcn_update_dpp(0, __float_as_int(x), 0x111, 0xf, 0xf, false)); }
; __device__ __forceinline__ float dpp_row_shr2(float x) { return __int_as_float(__builtin_amdgcn_update_dpp(0, __float_as_int(x), 0x112, 0xf, 0xf, false)); }
;     __device__ __forceinline__ void operator()(const f32x4 (&acc)[2][2][4][2], const Unit& u, int wr, int wc, int fr, int fq) const {
;     ...
;                     if (B > 0) { const LAS float* p = XG + ((B - 1) * 2) * 128 + chl; const f32x4 r0a = *(const LAS f32x4*)p, r0b = *(const LAS f32x4*)(p + 4), r1a = *(const LAS f32x4*)(p + 128), r1b = *(const LAS f32x4*)(p + 132);
; #pragma unroll
;                         for (int j = 0; j < 4; ++j) { q14[j] = r0a[j]; q14[4 + j] = r0b[j]; q15[j] = r1a[j]; q15[4 + j] = r1b[j]; } }
;                     else {
; #pragma unroll
;                         for (int j = 0; j < 8; ++j) { q14[j] = 0.f; q15[j] = 0.f; } }
;     ...
;                     float p1a[8], p2a[8];
; #pragma unroll
;                     for (int e = 0; e < 8; ++e) { const float pv = (e < 4) ? acc[ai][0][m - 1][0][e & 3] : acc[ai][0][m - 1][1][e & 3];
;                         const float s1 = dpp_row_shr1(g8[e]), s2 = dpp_row_shr2(g8[e]), r1 = dpp_row_ror1(pv), r2 = dpp_row_ror2(pv);
;                         p1a[e] = (fr >= 1) ? s1 : r1; p2a[e] = (fr >= 2) ? s2 : r2; }
; #pragma unroll
;                     for (int e = 0; e < 8; e += 2) { const f32x2 gt = (f32x2){w0[e], w0[e + 1]} * (f32x2){p2a[e], p2a[e + 1]} + (f32x2){w1[e], w1[e + 1]} * (f32x2){p1a[e], p1a[e + 1]} + (f32x2){w2[e], w2[e + 1]} * (f32x2){g8[e], g8[e + 1]} + (f32x2){bb[e], bb[e + 1]};
;                         const f32x2 r = gelu_tanh_mul2(gt, (f32x2){u8[e], u8[e + 1]}); o[e] = r.x; o[e + 1] = r.y; }
;                 }
;                 const int rloc = 128 * ai + 64 * wr + 16 * m + fr;
;                 if (!(B == 0 && m == 0 && fr < 2)) *(u32x4*)(ACT + (size_t)(u.pm * BM + rloc) * FF + chg) = pack8(o);
	v_mov_b32_dpp v118, v118 row_ror:1 row_mask:0xf bank_mask:0xf
	v_mov_b32_dpp v119, v119 row_ror:1 row_mask:0xf bank_mask:0xf
	v_mov_b32_dpp v120, v120 row_ror:1 row_mask:0xf bank_mask:0xf
	v_mov_b32_dpp v121, v121 row_ror:1 row_mask:0xf bank_mask:0xf
	v_mov_b32_dpp v122, v110 row_shr:2 row_mask:0xf bank_mask:0xf
	v_mov_b32_dpp v123, v111 row_shr:2 row_mask:0xf bank_mask:0xf
	v_mov_b32_dpp v124, v112 row_shr:2 row_mask:0xf bank_mask:0xf
	v_mov_b32_dpp v125, v113 row_shr:2 row_mask:0xf bank_mask:0xf
	v_mov_b32_dpp v118, v110 row_shr:1 row_mask:0xf bank_mask:0xf
	v_mov_b32_dpp v119, v111 row_shr:1 row_mask:0xf bank_mask:0xf
	v_mov_b32_dpp v120, v112 row_shr:1 row_mask:0xf bank_mask:0xf
	v_mov_b32_dpp v121, v113 row_shr:1 row_mask:0xf bank_mask:0xf
	v_pk_mul_f32 v[122:123], v[90:91], v[122:123]
	v_pk_fma_f32 v[118:119], v[94:95], v[118:119], v[122:123]
	v_pk_mul_f32 v[122:123], v[92:93], v[124:125]
	v_pk_fma_f32 v[110:111], v[110:111], v[98:99], v[118:119]
	v_pk_fma_f32 v[120:121], v[96:97], v[120:121], v[122:123]
	v_pk_add_f32 v[110:111], v[102:103], v[110:111]
	v_pk_fma_f32 v[112:113], v[112:113], v[100:101], v[120:121]
	v_pk_mul_f32 v[118:119], v[110:111], v[110:111]
	v_pk_add_f32 v[112:113], v[104:105], v[112:113]
	v_pk_fma_f32 v[118:119], v[118:119], s[78:79], 1.0 op_sel_hi:[1,0,0]
	v_pk_mul_f32 v[120:121], v[112:113], v[112:113]
	v_pk_mul_f32 v[118:119], v[110:111], v[118:119]
	v_pk_fma_f32 v[120:121], v[120:121], s[78:79], 1.0 op_sel_hi:[1,0,0]
	v_pk_mul_f32 v[118:119], v[118:119], s[24:25] op_sel_hi:[1,0]
	v_pk_mul_f32 v[120:121], v[112:113], v[120:121]
	v_exp_f32_e32 v118, v118
	v_exp_f32_e32 v119, v119
	v_pk_mul_f32 v[120:121], v[120:121], s[24:25] op_sel_hi:[1,0]
	v_exp_f32_e32 v120, v120
	v_exp_f32_e32 v121, v121
	v_mov_b32_dpp v126, v114 row_ror:2 row_mask:0xf bank_mask:0xf
	v_mov_b32_dpp v127, v115 row_ror:2 row_mask:0xf bank_mask:0xf
	v_mov_b32_dpp v128, v116 row_ror:2 row_mask:0xf bank_mask:0xf
	v_mov_b32_dpp v129, v117 row_ror:2 row_mask:0xf bank_mask:0xf
	v_mov_b32_dpp v114, v114 row_ror:1 row_mask:0xf bank_mask:0xf
	v_mov_b32_dpp v115, v115 row_ror:1 row_mask:0xf bank_mask:0xf
	v_mov_b32_dpp v116, v116 row_ror:1 row_mask:0xf bank_mask:0xf
	v_mov_b32_dpp v117, v117 row_ror:1 row_mask:0xf bank_mask:0xf
	v_mov_b32_dpp v126, v106 row_shr:2 row_mask:0xf bank_mask:0xf
	v_mov_b32_dpp v127, v107 row_shr:2 row_mask:0xf bank_mask:0xf
	v_mov_b32_dpp v128, v108 row_shr:2 row_mask:0xf bank_mask:0xf
	v_mov_b32_dpp v129, v109 row_shr:2 row_mask:0xf bank_mask:0xf
	v_mov_b32_dpp v114, v106 row_shr:1 row_mask:0xf bank_mask:0xf
	v_mov_b32_dpp v115, v107 row_shr:1 row_mask:0xf bank_mask:0xf
	v_mov_b32_dpp v116, v108 row_shr:1 row_mask:0xf bank_mask:0xf
	v_mov_b32_dpp v117, v109 row_shr:1 row_mask:0xf bank_mask:0xf
	v_pk_add_f32 v[118:119], v[118:119], 1.0 op_sel_hi:[1,0]
	v_rcp_f32_e32 v118, v118
	v_rcp_f32_e32 v119, v119
	v_pk_add_f32 v[120:121], v[120:121], 1.0 op_sel_hi:[1,0]
	v_rcp_f32_e32 v120, v120
	v_rcp_f32_e32 v121, v121
	v_pk_mul_f32 v[110:111], v[110:111], v[118:119]
	v_pk_mul_f32 v[86:87], v[86:87], v[110:111]
	v_pk_mul_f32 v[110:111], v[112:113], v[120:121]
	v_pk_mul_f32 v[112:113], v[66:67], v[126:127]
	v_pk_mul_f32 v[88:89], v[88:89], v[110:111]
	v_pk_fma_f32 v[112:113], v[70:71], v[114:115], v[112:113]
	v_pk_mul_f32 v[114:115], v[68:69], v[128:129]
	v_pk_fma_f32 v[106:107], v[106:107], v[74:75], v[112:113]
	v_pk_fma_f32 v[114:115], v[72:73], v[116:117], v[114:115]
	v_pk_add_f32 v[106:107], v[78:79], v[106:107]
	v_pk_fma_f32 v[108:109], v[108:109], v[76:77], v[114:115]
	v_pk_mul_f32 v[112:113], v[106:107], v[106:107]
	v_pk_add_f32 v[108:109], v[80:81], v[108:109]
	v_pk_fma_f32 v[112:113], v[112:113], s[78:79], 1.0 op_sel_hi:[1,0,0]
	v_pk_mul_f32 v[114:115], v[108:109], v[108:109]
	v_pk_mul_f32 v[112:113], v[106:107], v[112:113]
	v_pk_fma_f32 v[114:115], v[114:115], s[78:79], 1.0 op_sel_hi:[1,0,0]
	v_pk_mul_f32 v[112:113], v[112:113], s[24:25] op_sel_hi:[1,0]
	v_pk_mul_f32 v[114:115], v[108:109], v[114:115]
	v_exp_f32_e32 v112, v112
	v_exp_f32_e32 v113, v113
	v_pk_mul_f32 v[114:115], v[114:115], s[24:25] op_sel_hi:[1,0]
	v_mov_b32_e32 v110, 0
	v_exp_f32_e32 v114, v114
	v_exp_f32_e32 v115, v115
	v_pk_add_f32 v[112:113], v[112:113], 1.0 op_sel_hi:[1,0]
	v_mov_b32_e32 v111, 0
	v_rcp_f32_e32 v112, v112
	v_rcp_f32_e32 v113, v113
	v_pk_add_f32 v[114:115], v[114:115], 1.0 op_sel_hi:[1,0]
	v_pk_mul_f32 v[106:107], v[106:107], v[112:113]
	v_rcp_f32_e32 v114, v114
	v_rcp_f32_e32 v115, v115
	v_pk_mul_f32 v[106:107], v[82:83], v[106:107]
	v_mov_b32_e32 v112, 0
	v_mov_b32_e32 v113, 0
	v_pk_mul_f32 v[82:83], v[108:109], v[114:115]
	s_nop 0
	v_pk_mul_f32 v[108:109], v[84:85], v[82:83]
	v_cvt_pk_bf16_f32 v82, v86, v87
	v_or_b32_e32 v86, 48, v210
	v_mad_i64_i32 v[86:87], s[8:9], v86, s7, v[140:141]
	v_cvt_pk_bf16_f32 v83, v88, v89
	v_cvt_pk_bf16_f32 v84, v106, v107
	v_cvt_pk_bf16_f32 v85, v108, v109
	v_lshl_add_u64 v[86:87], v[86:87], 0, v[138:139]
	global_store_dwordx4 v[86:87], v[82:85], off
	v_mov_b32_e32 v109, 0
	v_mov_b32_e32 v108, 0
	v_mov_b32_e32 v107, 0
	v_mov_b32_e32 v106, 0
	v_mov_b32_e32 v85, 0
	v_mov_b32_e32 v84, 0
	v_mov_b32_e32 v83, 0
	v_mov_b32_e32 v82, 0
	v_mov_b32_e32 v86, 0
	v_mov_b32_e32 v87, 0
	v_mov_b32_e32 v88, 0
	v_mov_b32_e32 v89, 0
	s_cbranch_vccnz .LBB0_86
	ds_read_b128 v[82:85], v207
	ds_read_b128 v[106:109], v207 offset:16
	ds_read_b128 v[86:89], v207 offset:512
	ds_read_b128 v[110:113], v207 offset:528

; __device__ __forceinline__ u32x4 pack8(const float (&f)[8]) { u32x4 w; w.x = cvt_pk_bf16(f[0], f[1]); w.y = cvt_pk_bf16(f[2], f[3]); w.z = cvt_pk_bf16(f[4], f[5]); w.w = cvt_pk_bf16(f[6], f[7]); return w; }
; __device__ __forceinline__ float dpp_row_shr1(float x) { return __int_as_float(__builtin_amdgcn_update_dpp(0, __float_as_int(x), 0x111, 0xf, 0xf, false)); }
; __device__ __forceinline__ float dpp_row_shr2(float x) { return __int_as_float(__builtin_amdgcn_update_dpp(0, __float_as_int(x), 0x112, 0xf, 0xf, false)); }
; __device__ __forceinline__ float dpp_row_ror1(float x) { return __int_as_float(__builtin_amdgcn_update_dpp(0, __float_as_int(x), 0x121, 0xf, 0xf, false)); }
; __device__ __forceinline__ f32x2 gelu_tanh_mul2(f32x2 gt, f32x2 up) {
;     const f32x2 g2 = gt * gt;
;     const f32x2 t = gt * (g2 * 0.044715f + 1.0f);
;     const f32x2 sx = t * (-2.0f * 0.7978845608028654f * 1.4426950408889634f);
;     f32x2 e; e.x = __builtin_amdgcn_exp2f(sx.x); e.y = __builtin_amdgcn_exp2f(sx.y);
;     const f32x2 d = e + 1.0f;
;     f32x2 r; r.x = __builtin_amdgcn_rcpf(d.x); r.y = __builtin_amdgcn_rcpf(d.y);
;     return gt * r * up;
; }
;     __device__ __forceinline__ void operator()(const f32x4 (&acc)[2][2][4][2], const Unit& u, int wr, int wc, int fr, int fq) const {
;     ...
;                     float p1a[8], p2a[8];
; #pragma unroll
;                     for (int e = 0; e < 8; ++e) { const float pv = (e < 4) ? acc[ai][0][m - 1][0][e & 3] : acc[ai][0][m - 1][1][e & 3];
;                         const float s1 = dpp_row_shr1(g8[e]), s2 = dpp_row_shr2(g8[e]), r1 = dpp_row_ror1(pv), r2 = dpp_row_ror2(pv);
;                         p1a[e] = (fr >= 1) ? s1 : r1; p2a[e] = (fr >= 2) ? s2 : r2; }
; #pragma unroll
;                     for (int e = 0; e < 8; e += 2) { const f32x2 gt = (f32x2){w0[e], w0[e + 1]} * (f32x2){p2a[e], p2a[e + 1]} + (f32x2){w1[e], w1[e + 1]} * (f32x2){p1a[e], p1a[e + 1]} + (f32x2){w2[e], w2[e + 1]} * (f32x2){g8[e], g8[e + 1]} + (f32x2){bb[e], bb[e + 1]};
;                         const f32x2 r = gelu_tanh_mul2(gt, (f32x2){u8[e], u8[e + 1]}); o[e] = r.x; o[e + 1] = r.y; }
;                 }
;                 const int rloc = 128 * ai + 64 * wr + 16 * m + fr;
;                 if (!(B == 0 && m == 0 && fr < 2)) *(u32x4*)(ACT + (size_t)(u.pm * BM + rloc) * FF + chg) = pack8(o);
.LBB0_88:
	s_or_b64 exec, exec, s[30:31]
	s_nop 0
	s_nop 0
	s_nop 0
	v_mov_b32_dpp v58, v54 row_ror:2 row_mask:0xf bank_mask:0xf
	v_mov_b32_dpp v59, v55 row_ror:2 row_mask:0xf bank_mask:0xf
	v_mov_b32_dpp v60, v56 row_ror:2 row_mask:0xf bank_mask:0xf
	v_mov_b32_dpp v61, v57 row_ror:2 row_mask:0xf bank_mask:0xf
	v_mov_b32_dpp v54, v54 row_ror:1 row_mask:0xf bank_mask:0xf
	v_mov_b32_dpp v55, v55 row_ror:1 row_mask:0xf bank_mask:0xf
	v_mov_b32_dpp v56, v56 row_ror:1 row_mask:0xf bank_mask:0xf
	v_mov_b32_dpp v57, v57 row_ror:1 row_mask:0xf bank_mask:0xf
	v_mov_b32_dpp v58, v38 row_shr:2 row_mask:0xf bank_mask:0xf
	v_mov_b32_dpp v59, v39 row_shr:2 row_mask:0xf bank_mask:0xf
	v_mov_b32_dpp v60, v40 row_shr:2 row_mask:0xf bank_mask:0xf
	v_mov_b32_dpp v61, v41 row_shr:2 row_mask:0xf bank_mask:0xf
	v_mov_b32_dpp v54, v38 row_shr:1 row_mask:0xf bank_mask:0xf
	v_mov_b32_dpp v55, v39 row_shr:1 row_mask:0xf bank_mask:0xf
	v_mov_b32_dpp v56, v40 row_shr:1 row_mask:0xf bank_mask:0xf
	v_mov_b32_dpp v57, v41 row_shr:1 row_mask:0xf bank_mask:0xf
	v_pk_mul_f32 v[58:59], v[90:91], v[58:59]
	v_pk_mul_f32 v[60:61], v[92:93], v[60:61]
	v_pk_fma_f32 v[54:55], v[94:95], v[54:55], v[58:59]
	v_pk_fma_f32 v[56:57], v[96:97], v[56:57], v[60:61]
	v_pk_fma_f32 v[54:55], v[38:39], v[98:99], v[54:55]
	v_pk_fma_f32 v[56:57], v[40:41], v[100:101], v[56:57]
	v_pk_add_f32 v[54:55], v[102:103], v[54:55]
	v_pk_add_f32 v[56:57], v[104:105], v[56:57]
	v_pk_mul_f32 v[58:59], v[54:55], v[54:55]
	v_pk_mul_f32 v[60:61], v[56:57], v[56:57]
	v_pk_fma_f32 v[58:59], v[58:59], s[78:79], 1.0 op_sel_hi:[1,0,0]
	v_pk_fma_f32 v[60:61], v[60:61], s[78:79], 1.0 op_sel_hi:[1,0,0]
	v_pk_mul_f32 v[58:59], v[54:55], v[58:59]
	v_pk_mul_f32 v[60:61], v[56:57], v[60:61]
	v_pk_mul_f32 v[58:59], v[58:59], s[24:25] op_sel_hi:[1,0]
	v_pk_mul_f32 v[60:61], v[60:61], s[24:25] op_sel_hi:[1,0]
	v_exp_f32_e32 v58, v58
	v_exp_f32_e32 v59, v59
	v_exp_f32_e32 v60, v60
	v_exp_f32_e32 v61, v61
	v_mov_b32_dpp v62, v50 row_ror:2 row_mask:0xf bank_mask:0xf
	v_mov_b32_dpp v63, v51 row_ror:2 row_mask:0xf bank_mask:0xf
	v_mov_b32_dpp v64, v52 row_ror:2 row_mask:0xf bank_mask:0xf
	v_mov_b32_dpp v65, v53 row_ror:2 row_mask:0xf bank_mask:0xf
	v_mov_b32_dpp v50, v50 row_ror:1 row_mask:0xf bank_mask:0xf
	v_mov_b32_dpp v51, v51 row_ror:1 row_mask:0xf bank_mask:0xf
	v_mov_b32_dpp v52, v52 row_ror:1 row_mask:0xf bank_mask:0xf
	v_mov_b32_dpp v53, v53 row_ror:1 row_mask:0xf bank_mask:0xf
	v_mov_b32_dpp v62, v34 row_shr:2 row_mask:0xf bank_mask:0xf
	v_mov_b32_dpp v63, v35 row_shr:2 row_mask:0xf bank_mask:0xf
	v_mov_b32_dpp v64, v36 row_shr:2 row_mask:0xf bank_mask:0xf
	v_mov_b32_dpp v65, v37 row_shr:2 row_mask:0xf bank_mask:0xf
	v_mov_b32_dpp v50, v34 row_shr:1 row_mask:0xf bank_mask:0xf
	v_mov_b32_dpp v51, v35 row_shr:1 row_mask:0xf bank_mask:0xf
	v_mov_b32_dpp v52, v36 row_shr:1 row_mask:0xf bank_mask:0xf
	v_mov_b32_dpp v53, v37 row_shr:1 row_mask:0xf bank_mask:0xf
	s_waitcnt lgkmcnt(3)
	v_pk_add_f32 v[58:59], v[58:59], 1.0 op_sel_hi:[1,0]
	v_rcp_f32_e32 v58, v58
	v_rcp_f32_e32 v59, v59
	v_pk_add_f32 v[60:61], v[60:61], 1.0 op_sel_hi:[1,0]
	v_rcp_f32_e32 v60, v60
	v_rcp_f32_e32 v61, v61
	v_pk_mul_f32 v[54:55], v[54:55], v[58:59]
	v_pk_mul_f32 v[46:47], v[46:47], v[54:55]
	v_pk_mul_f32 v[54:55], v[56:57], v[60:61]
	v_pk_mul_f32 v[56:57], v[66:67], v[62:63]
	v_pk_mul_f32 v[58:59], v[68:69], v[64:65]
	v_pk_fma_f32 v[50:51], v[70:71], v[50:51], v[56:57]
	v_pk_fma_f32 v[52:53], v[72:73], v[52:53], v[58:59]
	v_pk_fma_f32 v[50:51], v[34:35], v[74:75], v[50:51]
	v_pk_fma_f32 v[52:53], v[36:37], v[76:77], v[52:53]
	v_pk_add_f32 v[50:51], v[78:79], v[50:51]
	v_pk_add_f32 v[52:53], v[80:81], v[52:53]
	v_pk_mul_f32 v[56:57], v[50:51], v[50:51]
	v_pk_mul_f32 v[58:59], v[52:53], v[52:53]
	v_pk_fma_f32 v[56:57], v[56:57], s[78:79], 1.0 op_sel_hi:[1,0,0]
	v_pk_fma_f32 v[58:59], v[58:59], s[78:79], 1.0 op_sel_hi:[1,0,0]
	v_pk_mul_f32 v[56:57], v[50:51], v[56:57]
	v_pk_mul_f32 v[58:59], v[52:53], v[58:59]
	v_pk_mul_f32 v[56:57], v[56:57], s[24:25] op_sel_hi:[1,0]
	v_pk_mul_f32 v[58:59], v[58:59], s[24:25] op_sel_hi:[1,0]
	v_exp_f32_e32 v56, v56
	v_exp_f32_e32 v57, v57
	v_exp_f32_e32 v58, v58
	v_exp_f32_e32 v59, v59
	v_readlane_b32 s8, v253, 57
	v_pk_add_f32 v[56:57], v[56:57], 1.0 op_sel_hi:[1,0]
	v_pk_mul_f32 v[48:49], v[48:49], v[54:55]
	v_rcp_f32_e32 v56, v56
	v_rcp_f32_e32 v57, v57
	v_pk_add_f32 v[58:59], v[58:59], 1.0 op_sel_hi:[1,0]
	v_readlane_b32 s9, v253, 58
	v_rcp_f32_e32 v58, v58
	v_rcp_f32_e32 v59, v59
	v_pk_mul_f32 v[50:51], v[50:51], v[56:57]
	v_mov_b32_e32 v54, v195
	v_pk_mul_f32 v[42:43], v[42:43], v[50:51]
	v_pk_mul_f32 v[50:51], v[52:53], v[58:59]
	v_mov_b32_e32 v52, v195
	v_pk_mul_f32 v[50:51], v[44:45], v[50:51]
	v_cvt_pk_bf16_f32 v44, v46, v47
	v_cvt_pk_bf16_f32 v45, v48, v49
	v_cvt_pk_bf16_f32 v46, v42, v43
	v_add_u32_e32 v48, 0x90, v210
	v_mov_b64_e32 v[42:43], s[8:9]
	v_mad_i64_i32 v[48:49], s[8:9], v48, s7, v[42:43]
	v_cvt_pk_bf16_f32 v47, v50, v51
	v_lshl_add_u64 v[48:49], v[48:49], 0, v[138:139]
	global_store_dwordx4 v[48:49], v[44:47], off
	s_nop 0
	s_nop 0
	s_nop 0
	s_nop 0
	v_mov_b32_dpp v44, v38 row_ror:2 row_mask:0xf bank_mask:0xf
	v_mov_b32_dpp v45, v39 row_ror:2 row_mask:0xf bank_mask:0xf
	v_mov_b32_dpp v46, v40 row_ror:2 row_mask:0xf bank_mask:0xf
	v_mov_b32_dpp v47, v41 row_ror:2 row_mask:0xf bank_mask:0xf
	v_mov_b32_dpp v38, v38 row_ror:1 row_mask:0xf bank_mask:0xf
	v_mov_b32_dpp v39, v39 row_ror:1 row_mask:0xf bank_mask:0xf
	v_mov_b32_dpp v40, v40 row_ror:1 row_mask:0xf bank_mask:0xf
	v_mov_b32_dpp v41, v41 row_ror:1 row_mask:0xf bank_mask:0xf
	v_mov_b32_dpp v44, v22 row_shr:2 row_mask:0xf bank_mask:0xf
; __device__ __forceinline__ u32x4 pack8(const float (&f)[8]) { u32x4 w; w.x = cvt_pk_bf16(f[0], f[1]); w.y = cvt_pk_bf16(f[2], f[3]); w.z = cvt_pk_bf16(f[4], f[5]); w.w = cvt_pk_bf16(f[6], f[7]); return w; }
; __device__ __forceinline__ float dpp_row_shr1(float x) { return __int_as_float(__builtin_amdgcn_update_dpp(0, __float_as_int(x), 0x111, 0xf, 0xf, false)); }
; __device__ __forceinline__ float dpp_row_shr2(float x) { return __int_as_float(__builtin_amdgcn_update_dpp(0, __float_as_int(x), 0x112, 0xf, 0xf, false)); }
; __device__ __forceinline__ float dpp_row_ror1(float x) { return __int_as_float(__builtin_amdgcn_update_dpp(0, __float_as_int(x), 0x121, 0xf, 0xf, false)); }
; __device__ __forceinline__ f32x2 gelu_tanh_mul2(f32x2 gt, f32x2 up) {
;     const f32x2 g2 = gt * gt;
;     const f32x2 t = gt * (g2 * 0.044715f + 1.0f);
;     const f32x2 sx = t * (-2.0f * 0.7978845608028654f * 1.4426950408889634f);
;     f32x2 e; e.x = __builtin_amdgcn_exp2f(sx.x); e.y = __builtin_amdgcn_exp2f(sx.y);
;     const f32x2 d = e + 1.0f;
;     f32x2 r; r.x = __builtin_amdgcn_rcpf(d.x); r.y = __builtin_amdgcn_rcpf(d.y);
;     return gt * r * up;
; }
;     __device__ __forceinline__ void operator()(const f32x4 (&acc)[2][2][4][2], const Unit& u, int wr, int wc, int fr, int fq) const {
;     ...
;                     float p1a[8], p2a[8];
; #pragma unroll
;                     for (int e = 0; e < 8; ++e) { const float pv = (e < 4) ? acc[ai][0][m - 1][0][e & 3] : acc[ai][0][m - 1][1][e & 3];
;                         const float s1 = dpp_row_shr1(g8[e]), s2 = dpp_row_shr2(g8[e]), r1 = dpp_row_ror1(pv), r2 = dpp_row_ror2(pv);
;                         p1a[e] = (fr >= 1) ? s1 : r1; p2a[e] = (fr >= 2) ? s2 : r2; }
; #pragma unroll
;                     for (int e = 0; e < 8; e += 2) { const f32x2 gt = (f32x2){w0[e], w0[e + 1]} * (f32x2){p2a[e], p2a[e + 1]} + (f32x2){w1[e], w1[e + 1]} * (f32x2){p1a[e], p1a[e + 1]} + (f32x2){w2[e], w2[e + 1]} * (f32x2){g8[e], g8[e + 1]} + (f32x2){bb[e], bb[e + 1]};
;                         const f32x2 r = gelu_tanh_mul2(gt, (f32x2){u8[e], u8[e + 1]}); o[e] = r.x; o[e + 1] = r.y; }
;                 }
;                 const int rloc = 128 * ai + 64 * wr + 16 * m + fr;
;                 if (!(B == 0 && m == 0 && fr < 2)) *(u32x4*)(ACT + (size_t)(u.pm * BM + rloc) * FF + chg) = pack8(o);
	v_mov_b32_dpp v45, v23 row_shr:2 row_mask:0xf bank_mask:0xf
	v_mov_b32_dpp v46, v24 row_shr:2 row_mask:0xf bank_mask:0xf
	v_mov_b32_dpp v47, v25 row_shr:2 row_mask:0xf bank_mask:0xf
	v_mov_b32_dpp v38, v22 row_shr:1 row_mask:0xf bank_mask:0xf
	v_mov_b32_dpp v39, v23 row_shr:1 row_mask:0xf bank_mask:0xf
	v_mov_b32_dpp v40, v24 row_shr:1 row_mask:0xf bank_mask:0xf
	v_mov_b32_dpp v41, v25 row_shr:1 row_mask:0xf bank_mask:0xf
	v_pk_mul_f32 v[44:45], v[90:91], v[44:45]
	v_pk_mul_f32 v[46:47], v[92:93], v[46:47]
	v_pk_fma_f32 v[38:39], v[94:95], v[38:39], v[44:45]
	v_pk_fma_f32 v[40:41], v[96:97], v[40:41], v[46:47]
	v_pk_fma_f32 v[38:39], v[22:23], v[98:99], v[38:39]
	v_pk_fma_f32 v[40:41], v[24:25], v[100:101], v[40:41]
	v_pk_add_f32 v[38:39], v[102:103], v[38:39]
	v_pk_add_f32 v[40:41], v[104:105], v[40:41]
	v_pk_mul_f32 v[44:45], v[38:39], v[38:39]
	v_pk_mul_f32 v[46:47], v[40:41], v[40:41]
	v_pk_fma_f32 v[44:45], v[44:45], s[78:79], 1.0 op_sel_hi:[1,0,0]
	v_pk_fma_f32 v[46:47], v[46:47], s[78:79], 1.0 op_sel_hi:[1,0,0]
	v_pk_mul_f32 v[44:45], v[38:39], v[44:45]
	v_pk_mul_f32 v[46:47], v[40:41], v[46:47]
	v_pk_mul_f32 v[44:45], v[44:45], s[24:25] op_sel_hi:[1,0]
	v_pk_mul_f32 v[46:47], v[46:47], s[24:25] op_sel_hi:[1,0]
	v_exp_f32_e32 v44, v44
	v_exp_f32_e32 v45, v45
	v_exp_f32_e32 v46, v46
	v_exp_f32_e32 v47, v47
	v_mov_b32_dpp v48, v34 row_ror:2 row_mask:0xf bank_mask:0xf
	v_mov_b32_dpp v49, v35 row_ror:2 row_mask:0xf bank_mask:0xf
	v_mov_b32_dpp v50, v36 row_ror:2 row_mask:0xf bank_mask:0xf
	v_mov_b32_dpp v51, v37 row_ror:2 row_mask:0xf bank_mask:0xf
	v_mov_b32_dpp v34, v34 row_ror:1 row_mask:0xf bank_mask:0xf
	v_mov_b32_dpp v35, v35 row_ror:1 row_mask:0xf bank_mask:0xf
	v_mov_b32_dpp v36, v36 row_ror:1 row_mask:0xf bank_mask:0xf
	v_mov_b32_dpp v37, v37 row_ror:1 row_mask:0xf bank_mask:0xf
	v_mov_b32_dpp v48, v18 row_shr:2 row_mask:0xf bank_mask:0xf
	v_mov_b32_dpp v49, v19 row_shr:2 row_mask:0xf bank_mask:0xf
	v_mov_b32_dpp v50, v20 row_shr:2 row_mask:0xf bank_mask:0xf
	v_mov_b32_dpp v51, v21 row_shr:2 row_mask:0xf bank_mask:0xf
	v_mov_b32_dpp v34, v18 row_shr:1 row_mask:0xf bank_mask:0xf
	v_mov_b32_dpp v35, v19 row_shr:1 row_mask:0xf bank_mask:0xf
	v_mov_b32_dpp v36, v20 row_shr:1 row_mask:0xf bank_mask:0xf
	v_mov_b32_dpp v37, v21 row_shr:1 row_mask:0xf bank_mask:0xf
	v_pk_add_f32 v[44:45], v[44:45], 1.0 op_sel_hi:[1,0]
	v_rcp_f32_e32 v44, v44
	v_rcp_f32_e32 v45, v45
	v_pk_add_f32 v[46:47], v[46:47], 1.0 op_sel_hi:[1,0]
	v_rcp_f32_e32 v46, v46
	v_rcp_f32_e32 v47, v47
	v_pk_mul_f32 v[38:39], v[38:39], v[44:45]
	v_pk_mul_f32 v[30:31], v[30:31], v[38:39]
	v_pk_mul_f32 v[38:39], v[40:41], v[46:47]
	v_pk_mul_f32 v[40:41], v[66:67], v[48:49]
	v_pk_mul_f32 v[44:45], v[68:69], v[50:51]
	v_pk_fma_f32 v[34:35], v[70:71], v[34:35], v[40:41]
	v_pk_fma_f32 v[36:37], v[72:73], v[36:37], v[44:45]
	v_pk_fma_f32 v[34:35], v[18:19], v[74:75], v[34:35]
	v_pk_fma_f32 v[36:37], v[20:21], v[76:77], v[36:37]
	v_pk_add_f32 v[34:35], v[78:79], v[34:35]
	v_pk_add_f32 v[36:37], v[80:81], v[36:37]
	v_pk_mul_f32 v[40:41], v[34:35], v[34:35]
	v_pk_mul_f32 v[44:45], v[36:37], v[36:37]
	v_pk_fma_f32 v[40:41], v[40:41], s[78:79], 1.0 op_sel_hi:[1,0,0]
	v_pk_fma_f32 v[44:45], v[44:45], s[78:79], 1.0 op_sel_hi:[1,0,0]
	v_pk_mul_f32 v[40:41], v[34:35], v[40:41]
	v_pk_mul_f32 v[44:45], v[36:37], v[44:45]
	v_pk_mul_f32 v[40:41], v[40:41], s[24:25] op_sel_hi:[1,0]
	v_pk_mul_f32 v[44:45], v[44:45], s[24:25] op_sel_hi:[1,0]
	v_exp_f32_e32 v40, v40
	v_exp_f32_e32 v41, v41
	v_exp_f32_e32 v44, v44
	v_exp_f32_e32 v45, v45
	v_pk_mul_f32 v[32:33], v[32:33], v[38:39]
	v_pk_add_f32 v[40:41], v[40:41], 1.0 op_sel_hi:[1,0]
	s_andn2_b64 vcc, exec, s[44:45]
	v_rcp_f32_e32 v40, v40
	v_rcp_f32_e32 v41, v41
	v_pk_add_f32 v[44:45], v[44:45], 1.0 op_sel_hi:[1,0]
	s_mov_b64 s[30:31], -1
	v_rcp_f32_e32 v44, v44
	v_rcp_f32_e32 v45, v45
	v_pk_mul_f32 v[34:35], v[34:35], v[40:41]
	s_nop 0
	v_pk_mul_f32 v[34:35], v[26:27], v[34:35]
	v_pk_mul_f32 v[26:27], v[36:37], v[44:45]
	s_nop 0
	v_pk_mul_f32 v[36:37], v[28:29], v[26:27]
	v_cvt_pk_bf16_f32 v26, v30, v31
	v_add_u32_e32 v30, 0xa0, v210
	v_mad_i64_i32 v[30:31], s[8:9], v30, s7, v[42:43]
	v_cvt_pk_bf16_f32 v27, v32, v33
	v_cvt_pk_bf16_f32 v28, v34, v35
	v_cvt_pk_bf16_f32 v29, v36, v37
	v_lshl_add_u64 v[30:31], v[30:31], 0, v[138:139]
	global_store_dwordx4 v[30:31], v[26:29], off
	s_nop 0
	s_nop 0
	s_nop 0
	s_nop 0
	v_mov_b32_dpp v26, v22 row_ror:2 row_mask:0xf bank_mask:0xf
	v_mov_b32_dpp v27, v23 row_ror:2 row_mask:0xf bank_mask:0xf
	v_mov_b32_dpp v28, v24 row_ror:2 row_mask:0xf bank_mask:0xf
	v_mov_b32_dpp v29, v25 row_ror:2 row_mask:0xf bank_mask:0xf
; #define PG8_BAR __builtin_amdgcn_s_barrier()
; template <class Epi>
; __device__ __forceinline__ void gemm_phase(LAS unsigned char* lds, const Gemm g, const Order& S, const Epi& E) {
;     ...
;     for (;;) {
;         const bool has_next = S.next(ui + 1, nxt);
;         const char* nA = has_next ? (const char*)(g.A + (size_t)nxt.g * g.gA) + (size_t)nxt.pm * tstepA : cA; const char* nB = has_next ? (const char*)(g.Bt + (size_t)nxt.g * g.gB) + (size_t)nxt.pn * tstepB : cB;
;         for (int t = 0; t < nt; t += 2) {
;             const bool last = (t == nt - 2);
;             const char* a1 = cA + (size_t)(t + 1) * kstep;
;             const char* a2 = last ? nA : cA + (size_t)(t + 2) * kstep; const char* b2 = last ? nB : cB + (size_t)(t + 2) * kstep;
;             const char* a3 = a2 + kstep; const char* b3 = b2 + kstep;
;             PG8_LDB(B0, 0, 0); PG8_LDB(B1, 0, 1); PG8_SCHED; PG8_LDA(At, 0, 0); PG8_STAGE(PG8_SA(1, 1), a1 + hstepA, voffA);
;             PG8_WAIT_V(8); PG8_WAIT_L(0); PG8_BAR; PG8_MMA(0, 0, At, B0); PG8_MMA(0, 1, At, B1); PG8_BAR; PG8_SCHED;
;             PG8_LDA(At, 0, 1); PG8_STAGE(PG8_SB(0, 0), b2, voffB); PG8_STAGE(PG8_SB(0, 1), b2 + hstepB, voffB); PG8_STAGE(PG8_SA(0, 0), a2, voffA);
;     __device__ __forceinline__ void operator()(const f32x4 (&acc)[2][2][4][2], const Unit& u, int wr, int wc, int fr, int fq) const {
;     ...
;                     float p1a[8], p2a[8];
; #pragma unroll
;                     for (int e = 0; e < 8; ++e) { const float pv = (e < 4) ? acc[ai][0][m - 1][0][e & 3] : acc[ai][0][m - 1][1][e & 3];
;                         const float s1 = dpp_row_shr1(g8[e]), s2 = dpp_row_shr2(g8[e]), r1 = dpp_row_ror1(pv), r2 = dpp_row_ror2(pv);
;                         p1a[e] = (fr >= 1) ? s1 : r1; p2a[e] = (fr >= 2) ? s2 : r2; }
; #pragma unroll
;                     for (int e = 0; e < 8; e += 2) { const f32x2 gt = (f32x2){w0[e], w0[e + 1]} * (f32x2){p2a[e], p2a[e + 1]} + (f32x2){w1[e], w1[e + 1]} * (f32x2){p1a[e], p1a[e + 1]} + (f32x2){w2[e], w2[e + 1]} * (f32x2){g8[e], g8[e + 1]} + (f32x2){bb[e], bb[e + 1]};
;                         const f32x2 r = gelu_tanh_mul2(gt, (f32x2){u8[e], u8[e + 1]}); o[e] = r.x; o[e + 1] = r.y; }
;                 }
;                 const int rloc = 128 * ai + 64 * wr + 16 * m + fr;
;                 if (!(B == 0 && m == 0 && fr < 2)) *(u32x4*)(ACT + (size_t)(u.pm * BM + rloc) * FF + chg) = pack8(o);
	v_mov_b32_dpp v22, v22 row_ror:1 row_mask:0xf bank_mask:0xf
	v_mov_b32_dpp v23, v23 row_ror:1 row_mask:0xf bank_mask:0xf
	v_mov_b32_dpp v24, v24 row_ror:1 row_mask:0xf bank_mask:0xf
	v_mov_b32_dpp v25, v25 row_ror:1 row_mask:0xf bank_mask:0xf
	v_mov_b32_dpp v26, v14 row_shr:2 row_mask:0xf bank_mask:0xf
	v_mov_b32_dpp v27, v15 row_shr:2 row_mask:0xf bank_mask:0xf
	v_mov_b32_dpp v28, v16 row_shr:2 row_mask:0xf bank_mask:0xf
	v_mov_b32_dpp v29, v17 row_shr:2 row_mask:0xf bank_mask:0xf
	v_mov_b32_dpp v22, v14 row_shr:1 row_mask:0xf bank_mask:0xf
	v_mov_b32_dpp v23, v15 row_shr:1 row_mask:0xf bank_mask:0xf
	v_mov_b32_dpp v24, v16 row_shr:1 row_mask:0xf bank_mask:0xf
	v_mov_b32_dpp v25, v17 row_shr:1 row_mask:0xf bank_mask:0xf
	v_pk_mul_f32 v[26:27], v[90:91], v[26:27]
	v_pk_fma_f32 v[22:23], v[94:95], v[22:23], v[26:27]
	v_pk_mul_f32 v[26:27], v[92:93], v[28:29]
	v_pk_fma_f32 v[14:15], v[14:15], v[98:99], v[22:23]
	v_pk_fma_f32 v[24:25], v[96:97], v[24:25], v[26:27]
	v_pk_add_f32 v[14:15], v[102:103], v[14:15]
	v_pk_fma_f32 v[16:17], v[16:17], v[100:101], v[24:25]
	v_pk_mul_f32 v[22:23], v[14:15], v[14:15]
	v_pk_add_f32 v[16:17], v[104:105], v[16:17]
	v_pk_fma_f32 v[22:23], v[22:23], s[78:79], 1.0 op_sel_hi:[1,0,0]
	v_pk_mul_f32 v[24:25], v[16:17], v[16:17]
	v_pk_mul_f32 v[22:23], v[14:15], v[22:23]
	v_pk_fma_f32 v[24:25], v[24:25], s[78:79], 1.0 op_sel_hi:[1,0,0]
	v_pk_mul_f32 v[22:23], v[22:23], s[24:25] op_sel_hi:[1,0]
	v_pk_mul_f32 v[24:25], v[16:17], v[24:25]
	v_exp_f32_e32 v22, v22
	v_exp_f32_e32 v23, v23
	v_pk_mul_f32 v[24:25], v[24:25], s[24:25] op_sel_hi:[1,0]
	v_exp_f32_e32 v24, v24
	v_exp_f32_e32 v25, v25
	v_mov_b32_dpp v30, v18 row_ror:2 row_mask:0xf bank_mask:0xf
	v_mov_b32_dpp v31, v19 row_ror:2 row_mask:0xf bank_mask:0xf
	v_mov_b32_dpp v32, v20 row_ror:2 row_mask:0xf bank_mask:0xf
	v_mov_b32_dpp v33, v21 row_ror:2 row_mask:0xf bank_mask:0xf
	v_mov_b32_dpp v18, v18 row_ror:1 row_mask:0xf bank_mask:0xf
	v_mov_b32_dpp v19, v19 row_ror:1 row_mask:0xf bank_mask:0xf
	v_mov_b32_dpp v20, v20 row_ror:1 row_mask:0xf bank_mask:0xf
	v_mov_b32_dpp v21, v21 row_ror:1 row_mask:0xf bank_mask:0xf
	v_mov_b32_dpp v30, v10 row_shr:2 row_mask:0xf bank_mask:0xf
	v_mov_b32_dpp v31, v11 row_shr:2 row_mask:0xf bank_mask:0xf
	v_mov_b32_dpp v32, v12 row_shr:2 row_mask:0xf bank_mask:0xf
	v_mov_b32_dpp v33, v13 row_shr:2 row_mask:0xf bank_mask:0xf
	v_mov_b32_dpp v18, v10 row_shr:1 row_mask:0xf bank_mask:0xf
	v_mov_b32_dpp v19, v11 row_shr:1 row_mask:0xf bank_mask:0xf
	v_mov_b32_dpp v20, v12 row_shr:1 row_mask:0xf bank_mask:0xf
	v_mov_b32_dpp v21, v13 row_shr:1 row_mask:0xf bank_mask:0xf
	v_pk_add_f32 v[22:23], v[22:23], 1.0 op_sel_hi:[1,0]
	v_rcp_f32_e32 v22, v22
	v_rcp_f32_e32 v23, v23
	v_pk_add_f32 v[24:25], v[24:25], 1.0 op_sel_hi:[1,0]
	v_rcp_f32_e32 v24, v24
	v_rcp_f32_e32 v25, v25
	v_pk_mul_f32 v[14:15], v[14:15], v[22:23]
	v_pk_mul_f32 v[6:7], v[6:7], v[14:15]
	v_pk_mul_f32 v[14:15], v[16:17], v[24:25]
	v_pk_mul_f32 v[16:17], v[66:67], v[30:31]
	v_pk_mul_f32 v[8:9], v[8:9], v[14:15]
	v_pk_fma_f32 v[16:17], v[70:71], v[18:19], v[16:17]
	v_pk_mul_f32 v[18:19], v[68:69], v[32:33]
	v_pk_fma_f32 v[10:11], v[10:11], v[74:75], v[16:17]
	v_pk_fma_f32 v[18:19], v[72:73], v[20:21], v[18:19]
	v_pk_add_f32 v[10:11], v[78:79], v[10:11]
	v_pk_fma_f32 v[12:13], v[12:13], v[76:77], v[18:19]
	v_pk_mul_f32 v[16:17], v[10:11], v[10:11]
	v_pk_add_f32 v[12:13], v[80:81], v[12:13]
	v_pk_fma_f32 v[16:17], v[16:17], s[78:79], 1.0 op_sel_hi:[1,0,0]
	v_pk_mul_f32 v[18:19], v[12:13], v[12:13]
	v_pk_mul_f32 v[16:17], v[10:11], v[16:17]
	v_pk_fma_f32 v[18:19], v[18:19], s[78:79], 1.0 op_sel_hi:[1,0,0]
	v_pk_mul_f32 v[16:17], v[16:17], s[24:25] op_sel_hi:[1,0]
	v_pk_mul_f32 v[18:19], v[12:13], v[18:19]
	v_exp_f32_e32 v16, v16
	v_exp_f32_e32 v17, v17
	v_pk_mul_f32 v[18:19], v[18:19], s[24:25] op_sel_hi:[1,0]
	v_pk_add_f32 v[16:17], v[16:17], 1.0 op_sel_hi:[1,0]
	v_exp_f32_e32 v18, v18
	v_exp_f32_e32 v19, v19
	v_rcp_f32_e32 v16, v16
	v_rcp_f32_e32 v17, v17
	v_pk_add_f32 v[18:19], v[18:19], 1.0 op_sel_hi:[1,0]
	s_nop 0
	v_rcp_f32_e32 v18, v18
	v_rcp_f32_e32 v19, v19
	v_pk_mul_f32 v[10:11], v[10:11], v[16:17]
	s_nop 0
	v_pk_mul_f32 v[10:11], v[2:3], v[10:11]
	v_pk_mul_f32 v[2:3], v[12:13], v[18:19]
	s_nop 0
	v_pk_mul_f32 v[12:13], v[4:5], v[2:3]
	v_cvt_pk_bf16_f32 v2, v6, v7
	v_add_u32_e32 v6, 0xb0, v210
	v_mad_i64_i32 v[6:7], s[8:9], v6, s7, v[42:43]
	v_lshl_add_u64 v[6:7], v[6:7], 0, v[138:139]
	v_cvt_pk_bf16_f32 v3, v8, v9
	v_cvt_pk_bf16_f32 v4, v10, v11
	v_cvt_pk_bf16_f32 v5, v12, v13
	global_store_dwordx4 v[6:7], v[2:5], off
	s_cbranch_vccnz .LBB0_67
	s_and_b64 vcc, exec, s[46:47]
	s_cbranch_vccnz .LBB0_66
	s_barrier
	s_branch .LBB0_66
